# v90 + phase 1 kv-latent epilogue: row-invariant gain vector loaded once before the row loops instead of load/wait at every row step
# baseline (speedup 1.0000x reference)
.LBB0_172:
	s_andn2_saveexec_b64 s[66:67], s[66:67]
	s_cbranch_execz .LBB0_194
	s_load_dwordx2 s[8:9], s[0:1], 0x48
	v_lshlrev_b32_e32 v0, 3, v140
	v_and_b32_e32 v10, 0x78, v0
	v_lshrrev_b32_e32 v11, 4, v140
	v_lshlrev_b32_e32 v0, 2, v10
	s_waitcnt lgkmcnt(0)
	v_lshl_add_u64 v[12:13], s[8:9], 0, v[0:1]
	global_load_dwordx4 v[240:243], v[12:13], off
	global_load_dwordx4 v[244:247], v[12:13], off offset:16
	v_mul_u32_u24_e32 v0, 0x410, v11
	v_and_b32_e32 v2, 15, v157
	v_add3_u32 v0, v159, v0, v158
	v_lshlrev_b32_e32 v2, 5, v2
	v_add3_u32 v23, v0, v2, 0
	v_add_u32_e32 v24, 0x400, v219
	v_add_u32_e32 v25, 0x800, v219
	v_add_u32_e32 v26, 0xc00, v219
	v_add_u32_e32 v27, 0x4000, v219
	v_add_u32_e32 v28, 0x4400, v219
	v_add_u32_e32 v29, 0x4800, v219
	v_add_u32_e32 v30, 0x4c00, v219
	v_add_u32_e32 v38, 0x8000, v219
	v_add_u32_e32 v31, 0x8400, v219
	v_add_u32_e32 v32, 0x8800, v219
	v_add_u32_e32 v33, 0x8c00, v219
	v_add_u32_e32 v39, 0xc000, v219
	v_add_u32_e32 v34, 0xc400, v219
	v_add_u32_e32 v36, 0xc800, v219
	v_add_u32_e32 v37, 0xcc00, v219
	v_add_u32_e32 v40, 0x9000, v219
	v_add_u32_e32 v41, 0xd000, v219
	v_add3_u32 v22, v11, s62, v156
	s_mov_b32 s70, 0
	v_mov_b32_e32 v42, v23
	s_barrier
	ds_write2_b32 v219, v163, v167 offset1:16
	ds_write2_b32 v24, v162, v166 offset0:4 offset1:20
	ds_write2_b32 v25, v161, v165 offset0:8 offset1:24
	ds_write2_b32 v26, v160, v164 offset0:12 offset1:28
	ds_write2_b32 v27, v171, v175 offset0:64 offset1:80
	ds_write2_b32 v28, v170, v174 offset0:68 offset1:84
	ds_write2_b32 v29, v169, v173 offset0:72 offset1:88
	ds_write2_b32 v30, v168, v172 offset0:76 offset1:92
	ds_write2_b32 v38, v180, v185 offset0:128 offset1:144
	ds_write2_b32 v31, v179, v184 offset0:132 offset1:148
	ds_write2_b32 v32, v178, v183 offset0:136 offset1:152
	ds_write2_b32 v33, v177, v182 offset0:140 offset1:156
	ds_write2_b32 v39, v189, v193 offset0:192 offset1:208
	ds_write2_b32 v34, v188, v192 offset0:196 offset1:212
	ds_write2_b32 v36, v187, v191 offset0:200 offset1:216
	ds_write2_b32 v37, v186, v190 offset0:204 offset1:220
	ds_write2_b32 v219, v128, v124 offset0:128 offset1:144
	ds_write2_b32 v24, v129, v125 offset0:132 offset1:148
	ds_write2_b32 v25, v130, v126 offset0:136 offset1:152
	ds_write2_b32 v26, v131, v127 offset0:140 offset1:156
	ds_write2_b32 v27, v120, v132 offset0:192 offset1:208
	ds_write2_b32 v28, v121, v117 offset0:196 offset1:212
	ds_write2_b32 v29, v122, v118 offset0:200 offset1:216
	ds_write2_b32 v30, v123, v119 offset0:204 offset1:220
	ds_write2_b32 v31, v134, v138 offset1:16
	ds_write2_b32 v32, v135, v139 offset0:4 offset1:20
	ds_write2_b32 v33, v136, v144 offset0:8 offset1:24
	ds_write2_b32 v40, v133, v137 offset0:12 offset1:28
	ds_write2_b32 v34, v146, v181 offset0:64 offset1:80
	ds_write2_b32 v36, v147, v149 offset0:68 offset1:84
	ds_write2_b32 v37, v176, v150 offset0:72 offset1:88
	ds_write2_b32 v41, v145, v148 offset0:76 offset1:92
	s_waitcnt lgkmcnt(0)
	s_barrier
	s_waitcnt vmcnt(0)
	s_branch .LBB0_176

.LBB0_176:
	ds_read_b128 v[2:5], v42
	ds_read_b128 v[6:9], v42 offset:16
	v_add_u32_e32 v16, s70, v22
	v_add_u32_e32 v43, s70, v11
	v_cmp_gt_i32_e32 vcc, s85, v16
	s_waitcnt lgkmcnt(1)
	v_mul_f32_e32 v0, v3, v3
	v_fmac_f32_e32 v0, v2, v2
	v_fmac_f32_e32 v0, v4, v4
	v_fmac_f32_e32 v0, v5, v5
	s_waitcnt lgkmcnt(0)
	v_fmac_f32_e32 v0, v6, v6
	v_fmac_f32_e32 v0, v7, v7
	v_fmac_f32_e32 v0, v8, v8
	v_fmac_f32_e32 v0, v9, v9
	v_lshlrev_b32_e32 v14, 2, v10
	s_nop 0
	v_add_f32_dpp v0, v0, v0 quad_perm:[1,0,3,2] row_mask:0xf bank_mask:0xf bound_ctrl:1
	s_nop 1
	v_add_f32_dpp v0, v0, v0 quad_perm:[2,3,0,1] row_mask:0xf bank_mask:0xf bound_ctrl:1
	s_nop 1
	v_add_f32_dpp v0, v0, v0 row_half_mirror row_mask:0xf bank_mask:0xf bound_ctrl:1
	s_nop 1
	v_mov_b32_dpp v15, v0 row_mirror row_mask:0xf bank_mask:0xf bound_ctrl:1
	s_and_saveexec_b64 s[68:69], vcc
	s_cbranch_execz .LBB0_180
	v_mov_b32_e32 v18, v244
	v_mov_b32_e32 v19, v245
	v_mov_b32_e32 v20, v246
	v_mov_b32_e32 v21, v247
	v_mov_b32_e32 v44, v240
	v_mov_b32_e32 v45, v241
	v_mov_b32_e32 v46, v242
	v_mov_b32_e32 v47, v243
	v_add_f32_e32 v0, v0, v15
	v_fmamk_f32 v0, v0, 0x3c000000, v215
	v_cmp_gt_f32_e32 vcc, s41, v0
	v_mul_f32_e32 v15, 0x4b800000, v0
	v_cmp_gt_i32_e64 s[8:9], s84, v16
	v_cndmask_b32_e32 v0, v0, v15, vcc
	v_rsq_f32_e32 v0, v0
	v_ashrrev_i32_e32 v17, 31, v16
	v_mul_f32_e32 v15, 0x45800000, v0
	v_cndmask_b32_e32 v0, v0, v15, vcc
	v_mov_b32_e32 v15, v1
	v_cmp_lt_i32_e32 vcc, s92, v16
	v_pk_mul_f32 v[18:19], v[0:1], v[18:19] op_sel_hi:[0,1]
	v_pk_mul_f32 v[44:45], v[0:1], v[44:45] op_sel_hi:[0,1]
	v_pk_mul_f32 v[2:3], v[2:3], v[44:45]
	v_pk_mul_f32 v[44:45], v[0:1], v[46:47] op_sel_hi:[0,1]
	v_pk_mul_f32 v[4:5], v[4:5], v[44:45]
	v_pk_mul_f32 v[6:7], v[6:7], v[18:19]
	v_pk_mul_f32 v[18:19], v[0:1], v[20:21] op_sel_hi:[0,1]
	v_add_u32_e32 v44, 0xffffc000, v16
	v_pk_mul_f32 v[8:9], v[8:9], v[18:19]
	v_cndmask_b32_e64 v19, 0, v17, s[8:9]
	v_cndmask_b32_e64 v18, v44, v16, s[8:9]
	v_cndmask_b32_e64 v0, v223, v224, s[8:9]
	v_lshl_add_u64 v[20:21], s[12:13], 0, v[0:1]
	v_lshlrev_b64 v[18:19], 9, v[18:19]
	v_lshl_add_u64 v[18:19], v[20:21], 0, v[18:19]
	v_lshl_add_u64 v[18:19], v[18:19], 0, v[14:15]
	global_store_dwordx4 v[18:19], v[2:5], off
	global_store_dwordx4 v[18:19], v[6:9], off offset:16
	v_mov_b64_e32 v[18:19], 0x6000000
	v_mov_b64_e32 v[20:21], v[16:17]
	s_and_saveexec_b64 s[8:9], vcc
	v_lshrrev_b32_e32 v0, 4, v44
	v_mul_lo_u32 v0, v0, s82
	v_and_or_b32 v0, v43, 11, v0
	v_add_u32_e32 v0, 0x400, v0
	v_mov_b64_e32 v[18:19], 0x6500000
	v_mov_b64_e32 v[20:21], v[0:1]
	s_or_b64 exec, exec, s[8:9]
	v_cvt_pk_bf16_f32 v2, v2, v3
	v_cvt_pk_bf16_f32 v3, v4, v5
	v_cvt_pk_bf16_f32 v4, v6, v7
	v_lshl_add_u64 v[6:7], s[14:15], 0, v[18:19]
	v_mad_u64_u32 v[6:7], s[8:9], v20, s40, v[6:7]
	v_mad_i32_i24 v7, v21, s40, v7
	v_lshlrev_b32_e32 v0, 1, v10
	v_cvt_pk_bf16_f32 v5, v8, v9
	v_lshl_add_u64 v[6:7], v[6:7], 0, v[0:1]
	global_store_dwordx4 v[6:7], v[2:5], off
.LBB0_180:
	s_or_b64 exec, exec, s[68:69]
	ds_read_b128 v[6:9], v42 offset:4160
	ds_read_b128 v[2:5], v42 offset:4176
	v_add_u32_e32 v18, 4, v16
	v_cmp_gt_i32_e32 vcc, s85, v18
	s_waitcnt lgkmcnt(1)
	v_mul_f32_e32 v0, v7, v7
	v_fmac_f32_e32 v0, v6, v6
	v_fmac_f32_e32 v0, v8, v8
	v_fmac_f32_e32 v0, v9, v9
	s_waitcnt lgkmcnt(0)
	v_fmac_f32_e32 v0, v2, v2
	v_fmac_f32_e32 v0, v3, v3
	v_fmac_f32_e32 v0, v4, v4
	v_fmac_f32_e32 v0, v5, v5
	s_nop 1
	v_add_f32_dpp v0, v0, v0 quad_perm:[1,0,3,2] row_mask:0xf bank_mask:0xf bound_ctrl:1
	s_nop 1
	v_add_f32_dpp v0, v0, v0 quad_perm:[2,3,0,1] row_mask:0xf bank_mask:0xf bound_ctrl:1
	s_nop 1
	v_add_f32_dpp v0, v0, v0 row_half_mirror row_mask:0xf bank_mask:0xf bound_ctrl:1
	s_nop 1
	v_mov_b32_dpp v15, v0 row_mirror row_mask:0xf bank_mask:0xf bound_ctrl:1
	s_and_saveexec_b64 s[68:69], vcc
	s_cbranch_execz .LBB0_175
	v_mov_b32_e32 v44, v240
	v_mov_b32_e32 v45, v241
	v_mov_b32_e32 v46, v242
	v_mov_b32_e32 v47, v243
	v_mov_b32_e32 v48, v244
	v_mov_b32_e32 v49, v245
	v_mov_b32_e32 v50, v246
	v_mov_b32_e32 v51, v247
	v_add_f32_e32 v0, v0, v15
	v_add_u32_e32 v20, 0xffffc004, v16
	v_ashrrev_i32_e32 v19, 31, v18
	v_fmamk_f32 v21, v0, 0x3c000000, v215
	v_cmp_gt_i32_e64 s[8:9], s84, v18
	v_mul_f32_e32 v142, 0x4b800000, v21
	v_mov_b32_e32 v15, v1
	v_cndmask_b32_e64 v17, 0, v19, s[8:9]
	v_cndmask_b32_e64 v16, v20, v18, s[8:9]
	v_cndmask_b32_e64 v0, v223, v224, s[8:9]
	v_cmp_gt_f32_e64 s[8:9], s41, v21
	v_lshl_add_u64 v[52:53], s[12:13], 0, v[0:1]
	v_lshlrev_b64 v[16:17], 9, v[16:17]
	v_cndmask_b32_e64 v0, v21, v142, s[8:9]
	v_rsq_f32_e32 v0, v0
	v_lshl_add_u64 v[16:17], v[52:53], 0, v[16:17]
	v_lshl_add_u64 v[16:17], v[16:17], 0, v[14:15]
	v_cmp_lt_i32_e32 vcc, s92, v18
	v_mul_f32_e32 v15, 0x45800000, v0
	v_cndmask_b32_e64 v0, v0, v15, s[8:9]
	v_pk_mul_f32 v[44:45], v[0:1], v[44:45] op_sel_hi:[0,1]
	v_pk_mul_f32 v[46:47], v[0:1], v[46:47] op_sel_hi:[0,1]
	v_pk_mul_f32 v[48:49], v[0:1], v[48:49] op_sel_hi:[0,1]
	v_pk_mul_f32 v[50:51], v[0:1], v[50:51] op_sel_hi:[0,1]
	v_pk_mul_f32 v[6:7], v[6:7], v[44:45]
	v_pk_mul_f32 v[8:9], v[8:9], v[46:47]
	v_pk_mul_f32 v[2:3], v[2:3], v[48:49]
	v_pk_mul_f32 v[4:5], v[4:5], v[50:51]
	global_store_dwordx4 v[16:17], v[6:9], off
	global_store_dwordx4 v[16:17], v[2:5], off offset:16
	v_mov_b64_e32 v[16:17], 0x6000000
	s_and_saveexec_b64 s[8:9], vcc
	s_cbranch_execz .LBB0_174
	v_lshrrev_b32_e32 v15, 4, v20
	v_add_u32_e32 v0, 4, v43
	v_mul_lo_u32 v15, v15, s82
	v_and_or_b32 v0, v0, 15, v15
	v_add_u32_e32 v0, 0x400, v0
	v_mov_b64_e32 v[16:17], 0x6500000
	v_mov_b64_e32 v[18:19], v[0:1]
	s_branch .LBB0_174

.LBB0_187:
	ds_read_b128 v[2:5], v23
	ds_read_b128 v[6:9], v23 offset:16
	v_add_u32_e32 v21, s70, v22
	v_add_u32_e32 v16, 0x80, v21
	v_add_u32_e32 v20, s70, v11
	s_waitcnt lgkmcnt(1)
	v_mul_f32_e32 v0, v3, v3
	v_fmac_f32_e32 v0, v2, v2
	v_fmac_f32_e32 v0, v4, v4
	v_fmac_f32_e32 v0, v5, v5
	s_waitcnt lgkmcnt(0)
	v_fmac_f32_e32 v0, v6, v6
	v_fmac_f32_e32 v0, v7, v7
	v_fmac_f32_e32 v0, v8, v8
	v_fmac_f32_e32 v0, v9, v9
	v_cmp_gt_i32_e32 vcc, s85, v16
	s_nop 0
	v_add_f32_dpp v0, v0, v0 quad_perm:[1,0,3,2] row_mask:0xf bank_mask:0xf bound_ctrl:1
	s_nop 1
	v_add_f32_dpp v0, v0, v0 quad_perm:[2,3,0,1] row_mask:0xf bank_mask:0xf bound_ctrl:1
	s_nop 1
	v_add_f32_dpp v0, v0, v0 row_half_mirror row_mask:0xf bank_mask:0xf bound_ctrl:1
	s_nop 1
	v_mov_b32_dpp v15, v0 row_mirror row_mask:0xf bank_mask:0xf bound_ctrl:1
	s_and_saveexec_b64 s[68:69], vcc
	s_cbranch_execz .LBB0_191
	v_mov_b32_e32 v24, v244
	v_mov_b32_e32 v25, v245
	v_mov_b32_e32 v26, v246
	v_mov_b32_e32 v27, v247
	v_mov_b32_e32 v28, v240
	v_mov_b32_e32 v29, v241
	v_mov_b32_e32 v30, v242
	v_mov_b32_e32 v31, v243
	v_add_f32_e32 v0, v0, v15
	v_fmamk_f32 v0, v0, 0x3c000000, v215
	v_cmp_gt_f32_e32 vcc, s41, v0
	v_mul_f32_e32 v15, 0x4b800000, v0
	v_cmp_gt_i32_e64 s[8:9], s84, v16
	v_cndmask_b32_e32 v0, v0, v15, vcc
	v_rsq_f32_e32 v0, v0
	v_ashrrev_i32_e32 v17, 31, v16
	v_mul_f32_e32 v15, 0x45800000, v0
	v_cndmask_b32_e32 v0, v0, v15, vcc
	v_mov_b32_e32 v15, v1
	v_cmp_lt_i32_e32 vcc, s92, v16
	v_pk_mul_f32 v[18:19], v[0:1], v[28:29] op_sel_hi:[0,1]
	v_pk_mul_f32 v[2:3], v[2:3], v[18:19]
	v_pk_mul_f32 v[18:19], v[0:1], v[30:31] op_sel_hi:[0,1]
	v_pk_mul_f32 v[4:5], v[4:5], v[18:19]
	v_pk_mul_f32 v[18:19], v[0:1], v[24:25] op_sel_hi:[0,1]
	v_pk_mul_f32 v[6:7], v[6:7], v[18:19]
	v_pk_mul_f32 v[18:19], v[0:1], v[26:27] op_sel_hi:[0,1]
	v_add_u32_e32 v24, 0xffffc080, v21
	v_pk_mul_f32 v[8:9], v[8:9], v[18:19]
	v_cndmask_b32_e64 v19, 0, v17, s[8:9]
	v_cndmask_b32_e64 v18, v24, v16, s[8:9]
	v_cndmask_b32_e64 v0, v223, v224, s[8:9]
	v_lshl_add_u64 v[26:27], s[12:13], 0, v[0:1]
	v_lshlrev_b64 v[18:19], 9, v[18:19]
	v_lshl_add_u64 v[18:19], v[26:27], 0, v[18:19]
	v_lshl_add_u64 v[18:19], v[18:19], 0, v[14:15]
	global_store_dwordx4 v[18:19], v[2:5], off
	global_store_dwordx4 v[18:19], v[6:9], off offset:16
	v_mov_b64_e32 v[18:19], 0x6000000
	s_and_saveexec_b64 s[8:9], vcc
	v_lshrrev_b32_e32 v0, 4, v24
	v_mul_lo_u32 v0, v0, s82
	v_and_or_b32 v0, v20, 11, v0
	v_add_u32_e32 v0, 0x400, v0
	v_mov_b64_e32 v[18:19], 0x6500000
	v_mov_b64_e32 v[16:17], v[0:1]
	s_or_b64 exec, exec, s[8:9]
	v_cvt_pk_bf16_f32 v2, v2, v3
	v_cvt_pk_bf16_f32 v3, v4, v5
	v_cvt_pk_bf16_f32 v4, v6, v7
	v_lshl_add_u64 v[6:7], s[14:15], 0, v[18:19]
	v_mad_u64_u32 v[6:7], s[8:9], v16, s40, v[6:7]
	v_mad_i32_i24 v7, v17, s40, v7
	v_lshlrev_b32_e32 v0, 1, v10
	v_cvt_pk_bf16_f32 v5, v8, v9
	v_lshl_add_u64 v[6:7], v[6:7], 0, v[0:1]
	global_store_dwordx4 v[6:7], v[2:5], off
.LBB0_191:
	s_or_b64 exec, exec, s[68:69]
	ds_read_b128 v[2:5], v23 offset:4160
	ds_read_b128 v[6:9], v23 offset:4176
	v_add_u32_e32 v16, 0x84, v21
	v_cmp_gt_i32_e32 vcc, s85, v16
	s_waitcnt lgkmcnt(1)
	v_mul_f32_e32 v0, v3, v3
	v_fmac_f32_e32 v0, v2, v2
	v_fmac_f32_e32 v0, v4, v4
	v_fmac_f32_e32 v0, v5, v5
	s_waitcnt lgkmcnt(0)
	v_fmac_f32_e32 v0, v6, v6
	v_fmac_f32_e32 v0, v7, v7
	v_fmac_f32_e32 v0, v8, v8
	v_fmac_f32_e32 v0, v9, v9
	s_nop 1
	v_add_f32_dpp v0, v0, v0 quad_perm:[1,0,3,2] row_mask:0xf bank_mask:0xf bound_ctrl:1
	s_nop 1
	v_add_f32_dpp v0, v0, v0 quad_perm:[2,3,0,1] row_mask:0xf bank_mask:0xf bound_ctrl:1
	s_nop 1
	v_add_f32_dpp v0, v0, v0 row_half_mirror row_mask:0xf bank_mask:0xf bound_ctrl:1
	s_nop 1
	v_mov_b32_dpp v15, v0 row_mirror row_mask:0xf bank_mask:0xf bound_ctrl:1
	s_and_saveexec_b64 s[68:69], vcc
	s_cbranch_execz .LBB0_186
	v_mov_b32_e32 v24, v244
	v_mov_b32_e32 v25, v245
	v_mov_b32_e32 v26, v246
	v_mov_b32_e32 v27, v247
	v_mov_b32_e32 v28, v240
	v_mov_b32_e32 v29, v241
	v_mov_b32_e32 v30, v242
	v_mov_b32_e32 v31, v243
	v_add_f32_e32 v0, v0, v15
	v_fmamk_f32 v0, v0, 0x3c000000, v215
	v_cmp_gt_f32_e32 vcc, s41, v0
	v_mul_f32_e32 v15, 0x4b800000, v0
	v_cmp_gt_i32_e64 s[8:9], s84, v16
	v_cndmask_b32_e32 v0, v0, v15, vcc
	v_rsq_f32_e32 v0, v0
	v_add_u32_e32 v21, 0xffffc084, v21
	v_ashrrev_i32_e32 v17, 31, v16
	v_mul_f32_e32 v15, 0x45800000, v0
	v_cndmask_b32_e32 v0, v0, v15, vcc
	v_mov_b32_e32 v15, v1
	v_cmp_lt_i32_e32 vcc, s92, v16
	v_pk_mul_f32 v[18:19], v[0:1], v[28:29] op_sel_hi:[0,1]
	v_pk_mul_f32 v[2:3], v[2:3], v[18:19]
	v_pk_mul_f32 v[18:19], v[0:1], v[30:31] op_sel_hi:[0,1]
	v_pk_mul_f32 v[4:5], v[4:5], v[18:19]
	v_pk_mul_f32 v[18:19], v[0:1], v[24:25] op_sel_hi:[0,1]
	v_pk_mul_f32 v[6:7], v[6:7], v[18:19]
	v_pk_mul_f32 v[18:19], v[0:1], v[26:27] op_sel_hi:[0,1]
	v_pk_mul_f32 v[8:9], v[8:9], v[18:19]
	v_cndmask_b32_e64 v19, 0, v17, s[8:9]
	v_cndmask_b32_e64 v18, v21, v16, s[8:9]
	v_cndmask_b32_e64 v0, v223, v224, s[8:9]
	v_lshl_add_u64 v[24:25], s[12:13], 0, v[0:1]
	v_lshlrev_b64 v[18:19], 9, v[18:19]
	v_lshl_add_u64 v[18:19], v[24:25], 0, v[18:19]
	v_lshl_add_u64 v[18:19], v[18:19], 0, v[14:15]
	global_store_dwordx4 v[18:19], v[2:5], off
	global_store_dwordx4 v[18:19], v[6:9], off offset:16
	v_mov_b64_e32 v[18:19], 0x6000000
	s_and_saveexec_b64 s[8:9], vcc
	s_cbranch_execz .LBB0_185
	v_lshrrev_b32_e32 v15, 4, v21
	v_add_u32_e32 v0, 4, v20
	v_mul_lo_u32 v15, v15, s82
	v_and_or_b32 v0, v0, 15, v15
	v_add_u32_e32 v0, 0x400, v0
	v_mov_b64_e32 v[18:19], 0x6500000
	v_mov_b64_e32 v[16:17], v[0:1]
	s_branch .LBB0_185
